# dn_scan: per-step outputs staged in LDS and stored as 2 global_store_dwordx4 per half and step (was 16 short stores); single loop body + hoisted LDS reads
# speedup vs baseline: 1.0125x; 1.0125x over previous
.LBB0_1377:
	s_or_b64 exec, exec, s[10:11]
	s_and_b64 s[8:9], s[2:3], exec
	s_cselect_b32 s9, s60, s62
	v_readlane_b32 s10, v254, 23
	s_cselect_b32 s8, s61, s63
	v_and_b32_e32 v50, 15, v39
	v_lshrrev_b32_e32 v52, 2, v39
	v_readlane_b32 s11, v254, 24
	s_add_u32 s9, s9, s10
	v_bfe_u32 v37, v39, 4, 2
	v_mul_u32_u24_e32 v51, 0x48, v50
	v_and_b32_e32 v52, 48, v52
	s_addc_u32 s10, s8, 0
	s_lshl_b32 s11, s19, 5
	v_lshl_add_u32 v51, v51, 1, s33
	v_lshlrev_b32_e32 v53, 1, v52
	v_lshlrev_b32_e32 v54, 2, v37
	v_lshlrev_b32_e32 v55, 3, v37
	v_lshlrev_b32_e32 v37, 4, v37
	s_add_u32 s8, s9, s11
	v_add3_u32 v86, v51, v53, v55
	v_or_b32_e32 v53, v52, v50
	v_add_u32_e32 v83, v51, v37
	s_addc_u32 s9, s10, 0
	v_lshlrev_b32_e32 v50, 1, v50
	v_mov_b32_e32 v51, v129
	v_lshl_add_u64 v[60:61], s[8:9], 0, v[50:51]
	v_and_b32_e32 v104, 0xff, v131
	v_lshrrev_b32_e32 v104, 1, v104
	v_lshlrev_b32_e32 v104, 9, v104
	v_and_b32_e32 v105, 1, v131
	v_lshl_or_b32 v104, v105, 4, v104
	v_mov_b32_e32 v105, 0
	v_lshl_add_u64 v[104:105], s[8:9], 0, v[104:105]
	v_lshrrev_b32_e32 v51, 1, v42
	v_mul_u32_u24_e32 v51, 48, v51
	v_lshl_add_u32 v49, v49, 1, s33
	v_add3_u32 v96, s33, v51, v36
	v_mul_u32_u24_e32 v36, 0x48, v44
	v_lshl_add_u32 v100, v36, 1, v49
	v_mul_u32_u24_e32 v36, 0x48, v45
	v_lshlrev_b32_e32 v36, 1, v36
	v_lshlrev_b32_e32 v43, 1, v43
	v_mul_u32_u24_e32 v53, 0x48, v53
	v_add3_u32 v99, s33, v36, v43
	v_mul_u32_u24_e32 v36, 0x48, v46
	v_lshlrev_b32_e32 v53, 1, v53
	v_lshl_add_u32 v98, v36, 1, v49
	v_mul_u32_u24_e32 v36, 0x48, v48
	v_add3_u32 v82, s33, v53, v37
	v_or_b32_e32 v37, v54, v52
	v_lshlrev_b32_e32 v36, 1, v36
	v_bitop3_b32 v48, v54, 63, v52 bitop3:0x36
	v_lshl_add_u32 v84, v37, 2, s33
	v_add3_u32 v97, s33, v36, v43
	v_mad_u32_u24 v43, v37, 48, s33
	v_or_b32_e32 v36, 1, v37
	v_mul_i32_i24_e32 v44, 0xffffffd4, v37
	v_or_b32_e32 v45, 2, v37
	v_or_b32_e32 v46, 3, v37
	v_cndmask_b32_e64 v85, v48, v37, s[2:3]
	v_bitop3_b32 v37, v54, 62, v52 bitop3:0x36
	v_cndmask_b32_e64 v81, v37, v36, s[2:3]
	v_bitop3_b32 v36, v54, 61, v52 bitop3:0x36
	v_cndmask_b32_e64 v80, v36, v45, s[2:3]
	v_bitop3_b32 v36, v54, 60, v52 bitop3:0x36
	v_cndmask_b32_e64 v78, v36, v46, s[2:3]
	v_and_b32_e32 v36, 0x1f80, v47
	v_and_b32_e32 v37, 1, v39
	v_or_b32_e32 v36, s13, v36
	v_lshlrev_b32_e32 v37, 4, v37
	v_readlane_b32 s8, v254, 11
	v_or3_b32 v36, v36, s11, v37
	v_mov_b32_e32 v37, s17
	v_readlane_b32 s9, v254, 12
	v_mov_b32_e32 v39, v129
	v_add_u32_e32 v95, s33, v38
	v_lshl_add_u64 v[70:71], s[8:9], 0, v[36:37]
	v_readlane_b32 s8, v254, 13
	v_add_u32_e32 v93, v43, v50
	v_lshl_add_u64 v[38:39], v[40:41], 0, v[38:39]
	v_readlane_b32 s9, v254, 14
	v_lshl_or_b32 v36, v42, 4, s13
	s_lshl_b32 s16, s16, 12
	v_add_u32_e32 v92, 48, v93
	v_add_u32_e32 v89, 0x60, v93
	v_add_u32_e32 v87, 0x90, v93
	v_lshl_add_u64 v[72:73], s[8:9], 0, v[38:39]
	v_lshl_add_u64 v[74:75], s[52:53], 0, v[36:37]
	v_lshl_add_u64 v[76:77], s[56:57], 0, v[36:37]
	s_movk_i32 s17, 0x42
	s_mov_b32 s19, -3
	s_mov_b64 s[8:9], 0
	v_add_u32_e32 v79, v43, v44
	v_mov_b32_e32 v67, v66
	v_mov_b32_e32 v68, v66
	v_mov_b32_e32 v69, v66
	v_and_b32_e32 v204, 15, v131
	v_lshlrev_b32_e32 v204, 1, v204
	v_add_u32_e32 v204, 0xc000, v204
	v_add_u32_e32 v204, s33, v204
	v_lshl_add_u32 v107, v85, 5, v204
	v_lshl_add_u32 v112, v81, 5, v204
	v_lshl_add_u32 v133, v80, 5, v204
	v_lshl_add_u32 v188, v78, 5, v204
	v_and_b32_e32 v204, 0xff, v131
	v_lshlrev_b32_e32 v204, 4, v204
	v_add_u32_e32 v204, 0xc000, v204
	v_add_u32_e32 v204, s33, v204
.LBB0_1378:
	s_barrier
	s_waitcnt vmcnt(7)
	ds_write_b128 v100, v[4:7]
	s_waitcnt vmcnt(6)
	ds_write_b128 v100, v[8:11] offset:9216
	s_waitcnt vmcnt(5)
	ds_write_b128 v100, v[24:27] offset:18432
	s_waitcnt vmcnt(4)
	ds_write_b16 v99, v12 offset:27648
	ds_write_b16_d16_hi v99, v12 offset:27792
	ds_write_b16 v99, v13 offset:27936
	ds_write_b16_d16_hi v99, v13 offset:28080
	ds_write_b16 v99, v14 offset:28224
	ds_write_b16_d16_hi v99, v14 offset:28368
	ds_write_b16 v99, v15 offset:28512
	ds_write_b16_d16_hi v99, v15 offset:28656
	s_waitcnt vmcnt(3)
	ds_write_b128 v98, v[16:19]
	s_waitcnt vmcnt(2)
	ds_write_b128 v98, v[20:23] offset:9216
	s_waitcnt vmcnt(1)
	ds_write_b128 v98, v[32:35] offset:18432
	s_waitcnt vmcnt(0)
	ds_write_b16 v97, v28 offset:27648
	ds_write_b16_d16_hi v97, v28 offset:27792
	ds_write_b16 v97, v29 offset:27936
	ds_write_b16_d16_hi v97, v29 offset:28080
	ds_write_b16 v97, v30 offset:28224
	ds_write_b16_d16_hi v97, v30 offset:28368
	ds_write_b16 v97, v31 offset:28512
	ds_write_b16_d16_hi v97, v31 offset:28656
	s_and_saveexec_b64 s[10:11], s[4:5]
	ds_write_b128 v96, v[0:3] offset:36864
	s_or_b64 exec, exec, s[10:11]
	s_and_saveexec_b64 s[10:11], s[6:7]
	ds_write_b32 v95, v94 offset:46848
	s_or_b64 exec, exec, s[10:11]
	v_cvt_pk_bf16_f32 v4, v66, v67
	v_cvt_pk_bf16_f32 v5, v68, v69
	ds_write_b64 v86, v[4:5] offset:39936
	s_cmp_gt_i32 s19, -3
	s_cbranch_scc0 .Lscan_nofl
	s_and_saveexec_b64 s[10:11], s[4:5]
	ds_read_b128 v[36:39], v204
	s_lshl_b32 s26, s24, 9
	s_mov_b32 s27, 0
	v_lshl_add_u64 v[150:151], v[104:105], 0, s[26:27]
	s_waitcnt lgkmcnt(0)
	global_store_dwordx4 v[150:151], v[36:39], off
	s_or_b64 exec, exec, s[10:11]
.Lscan_nofl:
	s_waitcnt lgkmcnt(0)
	s_barrier
	v_mov_b32_e32 v102, s33
	v_add_u32_e32 v65, 0xb704, v79
	ds_read_b128 v[36:39], v82
	ds_read_b128 v[40:43], v83 offset:39936
	ds_read_b128 v[44:47], v82 offset:64
	ds_read_b128 v[48:51], v83 offset:40000
	ds_read_b32 v101, v102 offset:47100
	ds_read_b32 v208, v84 offset:46848
	ds_read2_b32 v[210:211], v65 offset1:1
	ds_read_b32 v209, v79 offset:46860
	ds_read_u16 v212, v93 offset:36864
	ds_read_u16 v213, v92 offset:36864
	ds_read_u16 v214, v89 offset:36864
	ds_read_u16 v215, v87 offset:36864
	s_cmp_gt_i32 s19, 63
	s_cbranch_scc1 .Lscan_skip
	s_add_i32 s10, s19, 3
	s_cmp_gt_u32 s10, 2
	s_mov_b64 s[10:11], -1
	s_cbranch_scc0 .LBB0_1384
	s_and_b64 s[10:11], s[2:3], exec
	s_cselect_b32 s13, s19, s17
	s_mov_b64 s[10:11], 0

.Lscan_skip:
	s_add_i32 s17, s17, -1
	s_add_i32 s19, s19, 1
	s_add_u32 s8, s8, 0x2000
	s_addc_u32 s9, s9, 0
	v_lshl_add_u64 v[72:73], v[72:73], 0, s[88:89]
	s_waitcnt lgkmcnt(8)
	v_mfma_f32_16x16x32_bf16 v[36:39], v[36:39], v[40:43], 0
	v_mfma_f32_16x16x32_bf16 v[36:39], v[44:47], v[48:51], v[36:39]
	ds_read_b128 v[216:219], v82 offset:18432
	ds_read_b128 v[220:223], v82 offset:18496
	ds_read_b128 v[224:227], v82 offset:9216
	ds_read_b128 v[228:231], v82 offset:9280
	ds_read_b128 v[232:235], v82 offset:27648
	ds_read_b128 v[236:239], v82 offset:27712
	s_waitcnt lgkmcnt(6)
	v_sub_f32_e32 v52, v101, v208
	v_sub_f32_e32 v53, v101, v210
	v_sub_f32_e32 v54, v101, v211
	v_sub_f32_e32 v55, v101, v209
	v_mul_f32_e32 v52, 0x3fb8aa3b, v52
	v_mul_f32_e32 v53, 0x3fb8aa3b, v53
	v_mul_f32_e32 v54, 0x3fb8aa3b, v54
	v_mul_f32_e32 v55, 0x3fb8aa3b, v55
	v_exp_f32_e32 v52, v52
	v_exp_f32_e32 v53, v53
	v_exp_f32_e32 v54, v54
	v_exp_f32_e32 v55, v55
	v_lshlrev_b32_e32 v212, 16, v212
	v_lshlrev_b32_e32 v213, 16, v213
	v_lshlrev_b32_e32 v214, 16, v214
	v_lshlrev_b32_e32 v215, 16, v215
	s_waitcnt lgkmcnt(4)
	v_mfma_f32_16x16x32_bf16 v[108:111], v[216:219], v[40:43], 0
	v_mfma_f32_16x16x32_bf16 v[108:111], v[220:223], v[48:51], v[108:111]
	v_pk_add_f32 v[36:37], v[212:213], v[36:37] neg_lo:[0,1] neg_hi:[0,1]
	v_pk_add_f32 v[38:39], v[214:215], v[38:39] neg_lo:[0,1] neg_hi:[0,1]
	v_pk_mul_f32 v[56:57], v[36:37], v[52:53]
	v_pk_mul_f32 v[58:59], v[38:39], v[54:55]
	v_cvt_pk_bf16_f32 v102, v36, v37
	v_cvt_pk_bf16_f32 v103, v38, v39
	ds_write_b64 v86, v[102:103] offset:42240
	v_cvt_pk_bf16_f32 v56, v56, v57
	v_cvt_pk_bf16_f32 v57, v58, v59
	ds_write_b64 v86, v[56:57] offset:44544
	v_mul_f32_e32 v212, 0x3fb8aa3b, v208
	v_mul_f32_e32 v213, 0x3fb8aa3b, v210
	v_mul_f32_e32 v214, 0x3fb8aa3b, v211
	v_mul_f32_e32 v215, 0x3fb8aa3b, v209
	v_mul_f32_e32 v248, 0x3fb8aa3b, v101
	v_exp_f32_e32 v212, v212
	v_exp_f32_e32 v213, v213
	v_exp_f32_e32 v214, v214
	v_exp_f32_e32 v215, v215
	v_exp_f32_e32 v248, v248
	s_waitcnt lgkmcnt(0)
	s_barrier
	ds_read_b128 v[52:55], v83 offset:42240
	ds_read_b128 v[56:59], v83 offset:42304
	ds_read_b128 v[240:243], v83 offset:44544
	ds_read_b128 v[244:247], v83 offset:44608
	s_waitcnt lgkmcnt(3)
	v_mfma_f32_16x16x32_bf16 v[224:227], v[224:227], v[52:55], 0
	s_waitcnt lgkmcnt(2)
	v_mfma_f32_16x16x32_bf16 v[224:227], v[228:231], v[56:59], v[224:227]
	s_waitcnt lgkmcnt(1)
	v_mfma_f32_16x16x32_bf16 v[232:235], v[232:235], v[240:243], 0
	s_waitcnt lgkmcnt(0)
	v_mfma_f32_16x16x32_bf16 v[232:235], v[236:239], v[244:247], v[232:235]
	s_nop 4
	v_fma_f32 v40, v108, v212, v224
	v_fma_f32 v41, v109, v213, v225
	v_fma_f32 v42, v110, v214, v226
	v_fma_f32 v43, v111, v215, v227
	v_bfe_u32 v52, v40, 16, 1
	v_bfe_u32 v53, v41, 16, 1
	v_bfe_u32 v54, v42, 16, 1
	v_bfe_u32 v55, v43, 16, 1
	v_add3_u32 v40, v40, v52, s42
	v_add3_u32 v41, v41, v53, s42
	v_add3_u32 v42, v42, v54, s42
	v_add3_u32 v43, v43, v55, s42
	ds_write_b16_d16_hi v107, v40
	ds_write_b16_d16_hi v112, v41
	ds_write_b16_d16_hi v133, v42
	ds_write_b16_d16_hi v188, v43
	s_waitcnt lgkmcnt(0)
	v_pk_fma_f32 v[68:69], v[68:69], v[248:249], v[234:235] op_sel_hi:[1,0,1]
	v_pk_fma_f32 v[66:67], v[66:67], v[248:249], v[232:233] op_sel_hi:[1,0,1]
	s_cmp_lg_u32 s8, 0x88000
	s_mov_b32 s24, s15
	s_cbranch_scc0 .Lscan_done
	s_mov_b32 s15, s13
	s_branch .LBB0_1378
.Lscan_done:
	s_waitcnt lgkmcnt(0)
	s_barrier
	s_and_saveexec_b64 s[10:11], s[4:5]
	ds_read_b128 v[36:39], v204
	s_lshl_b32 s26, s24, 9
	s_mov_b32 s27, 0
	v_lshl_add_u64 v[150:151], v[104:105], 0, s[26:27]
	s_waitcnt lgkmcnt(0)
	global_store_dwordx4 v[150:151], v[36:39], off
	s_or_b64 exec, exec, s[10:11]
	v_readlane_b32 s0, v252, 26
	s_nop 1
	s_add_i32 s12, s0, s12
	s_branch .LBB0_1372
